# v26 + GEMM accumulator zeroing with 64 v_mov_b64 instead of 128 v_mov_b32 per tile
# speedup vs baseline: 1.0054x; 1.0054x over previous
; template <class Epi>
; __device__ __forceinline__ void gemm_phase(LAS unsigned char* lds, const Gemm g, const Epi& E) {
;     ...
; #pragma unroll
;     for (int a = 0; a < 2; ++a)
; #pragma unroll
;       for (int b = 0; b < 2; ++b)
; #pragma unroll
;         for (int m = 0; m < 4; ++m)
; #pragma unroll
;           for (int n = 0; n < 2; ++n) acc[a][b][m][n] = (f32x4){0.f, 0.f, 0.f, 0.f};
.LBB0_578:
	s_add_u32 s2, s2, 0x80
	s_addc_u32 s3, s3, 0
	s_add_u32 s38, s26, 0x100
	v_mov_b64_e32 v[0:1], 0
	v_mov_b64_e32 v[2:3], 0
	v_mov_b64_e32 v[4:5], 0
	v_mov_b64_e32 v[6:7], 0
	v_mov_b64_e32 v[8:9], 0
	v_mov_b64_e32 v[10:11], 0
	v_mov_b64_e32 v[12:13], 0
	v_mov_b64_e32 v[14:15], 0
	v_mov_b64_e32 v[16:17], 0
	v_mov_b64_e32 v[18:19], 0
	v_mov_b64_e32 v[20:21], 0
	v_mov_b64_e32 v[22:23], 0
	v_mov_b64_e32 v[24:25], 0
	v_mov_b64_e32 v[26:27], 0
	v_mov_b64_e32 v[28:29], 0
	v_mov_b64_e32 v[30:31], 0
	v_mov_b64_e32 v[32:33], 0
	v_mov_b64_e32 v[34:35], 0
	v_mov_b64_e32 v[36:37], 0
	v_mov_b64_e32 v[38:39], 0
	v_mov_b64_e32 v[40:41], 0
	v_mov_b64_e32 v[42:43], 0
	v_mov_b64_e32 v[44:45], 0
	v_mov_b64_e32 v[46:47], 0
	v_mov_b64_e32 v[48:49], 0
	v_mov_b64_e32 v[50:51], 0
	v_mov_b64_e32 v[52:53], 0
	v_mov_b64_e32 v[54:55], 0
	v_mov_b64_e32 v[56:57], 0
	v_mov_b64_e32 v[58:59], 0
	v_mov_b64_e32 v[60:61], 0
	v_mov_b64_e32 v[62:63], 0
	v_mov_b64_e32 v[64:65], 0
	v_mov_b64_e32 v[66:67], 0
	v_mov_b64_e32 v[68:69], 0
	v_mov_b64_e32 v[70:71], 0
	v_mov_b64_e32 v[72:73], 0
	v_mov_b64_e32 v[74:75], 0
	v_mov_b64_e32 v[76:77], 0
	v_mov_b64_e32 v[78:79], 0
	v_mov_b64_e32 v[80:81], 0
	v_mov_b64_e32 v[82:83], 0
	v_mov_b64_e32 v[84:85], 0
	v_mov_b64_e32 v[86:87], 0
	v_mov_b64_e32 v[88:89], 0
	v_mov_b64_e32 v[90:91], 0
	v_mov_b64_e32 v[92:93], 0
	v_mov_b64_e32 v[94:95], 0
	v_mov_b64_e32 v[96:97], 0
	v_mov_b64_e32 v[98:99], 0
	v_mov_b64_e32 v[100:101], 0
	v_mov_b64_e32 v[102:103], 0
	v_mov_b64_e32 v[104:105], 0
	v_mov_b64_e32 v[106:107], 0
	v_mov_b64_e32 v[108:109], 0
	v_mov_b64_e32 v[110:111], 0
	v_mov_b64_e32 v[112:113], 0
	v_mov_b64_e32 v[114:115], 0
	v_mov_b64_e32 v[116:117], 0
	v_mov_b64_e32 v[118:119], 0
	v_mov_b64_e32 v[120:121], 0
	v_mov_b64_e32 v[122:123], 0
	v_mov_b64_e32 v[124:125], 0
	v_mov_b64_e32 v[126:127], 0
	s_addc_u32 s39, s27, 0
	s_mov_b32 s26, 0
